# t5 + P5 K tile LDS image with 4-bit XOR swizzle (conflict-free ds_read_b128)
# speedup vs baseline: 1.0085x; 1.0037x over previous
; template <class Epi>
; __device__ __forceinline__ void attn_rs_body(const bf16* __restrict__ Qb, const bf16* __restrict__ Kc, const bf16* __restrict__ V0c, const bf16* __restrict__ V1c, int NT, char* lds, const Epi& epi) {
;     ...
;     for (int i = 0; i < 4; ++i) { const int r = 16 * pw + 4 * i + (lane >> 4), c = (lane & 15) ^ (r & 7); kdo[i] = (long)r * 128 + c * 8; }
;     ...
;     const int kfb = (int)(uintptr_t)(lds + RS_K) + r32 * 256, ksw = (r32 & 7) << 4, hi16 = hi * 16;
; __device__ __forceinline__ void p5_attn_odd(const Args& a, unsigned char* lds_g) {
;     ...
;     for (int item = blockIdx.x; item < 2048; item += G) {
;         const int i = item >> 8, xcd = item & 7, slot = (item & 255) >> 3, combo = (i >> 1) * 8 + xcd, qb = (i & 1) * 32 + slot, h = combo >> 1, t = combo & 1;
;         const int tok0 = qb * 128;
;         att::EpiPart ep{op + (size_t)t * S_ * DM + (size_t)(tok0 + (wid & 3) * 32) * DM + h * 256};
;         att::attn_rs_body(proj + (2 * h + t) * CHS + (size_t)tok0 * 128, proj + (32 + 2 * h + t) * CHS, proj + (64 + 2 * h) * CHS, proj + (65 + 2 * h) * CHS,
;                           S_ / 64, (char*)lds_g, ep);
.LBB0_492:
	s_cmp_lt_i32 s92, 6
	s_cselect_b64 s[2:3], -1, 0
	s_and_b64 s[6:7], s[2:3], s[0:1]
	s_andn2_b64 vcc, exec, s[6:7]
	s_cbranch_vccnz .LBB0_519
	s_cmpk_gt_i32 s96, 0x7ff
	s_cbranch_scc1 .LBB0_518
	s_add_u32 s33, s90, 0x17000000
	s_addc_u32 s54, s91, 0
	v_lshlrev_b32_e32 v0, 11, v162
	s_add_u32 s55, s90, 0x33000000
	v_and_b32_e32 v0, 0x60000, v0
	s_addc_u32 s56, s91, 0
	s_mov_b32 s9, 0
	s_mov_b64 s[10:11], 0x80
	s_mov_b64 s[12:13], 0x17004000
	s_mov_b64 s[14:15], 0x17204000
	s_mov_b64 s[16:17], 0x17004080
	s_mov_b64 s[18:19], 0x17204080
	v_lshlrev_b32_e32 v163, 1, v0
	s_waitcnt lgkmcnt(0)
	v_mov_b32_e32 v1, 0
	s_mov_b64 s[20:21], 0x16000
	s_mov_b64 s[22:23], 0x20000
	s_mov_b64 s[24:25], 0x22000
	s_mov_b64 s[26:27], 0x24000
	s_mov_b64 s[28:29], 0x26000
	s_mov_b64 s[30:31], 0x30000
	s_mov_b64 s[34:35], 0x32000
	s_mov_b64 s[36:37], 0x34000
	s_mov_b64 s[38:39], 0x36000
	s_movk_i32 s57, 0xf0
	s_mov_b64 s[40:41], 0x400
	s_mov_b64 s[42:43], 0x800
	s_mov_b64 s[44:45], 0xc00
	s_movk_i32 s58, 0x60
	s_movk_i32 s59, 0xa0
	s_movk_i32 s60, 0xe0
	s_mov_b32 s61, 0x42b504f3
	s_mov_b32 s62, s96
	s_branch .LBB0_497

; #define RS_BAR() do { asm volatile("s_waitcnt lgkmcnt(0)" ::: "memory"); __builtin_amdgcn_s_barrier(); asm volatile("" ::: "memory"); } while (0)
; #define KDMA(t, kb) do { _Pragma("unroll") for (int i = 0; i < 4; ++i) \
;       __builtin_amdgcn_global_load_lds((const unsigned*)(Kc + (long)(t) * 8192 + kdo[i]), (ATT_LAS unsigned*)(lds + RS_K + (kb) * 16384 + (pw * 4 + i) * 1024), 16, 0, 0); } while (0)
; #define VM0() asm volatile("s_waitcnt vmcnt(0)" ::: "memory")
; #define VM0() asm volatile("s_waitcnt vmcnt(0)" ::: "memory")
; template <class Epi>
; __device__ __forceinline__ void attn_rs_body(const bf16* __restrict__ Qb, const bf16* __restrict__ Kc, const bf16* __restrict__ V0c, const bf16* __restrict__ V1c, int NT, char* lds, const Epi& epi) {
;     ...
;     long kdo[4];
; #pragma unroll
;     for (int i = 0; i < 4; ++i) { const int r = 16 * pw + 4 * i + (lane >> 4), c = (lane & 15) ^ (r & 7); kdo[i] = (long)r * 128 + c * 8; }
;     ...
;     const int kfb = (int)(uintptr_t)(lds + RS_K) + r32 * 256, ksw = (r32 & 7) << 4, hi16 = hi * 16;
;     ...
;     float m_reg = -1e30f, l_reg = 0.f;
;     f32x16 pA0, pA1, pB0, pB1;
;     KDMA(0, 0); KDMA(1, 1); VM0();
;     RS_BAR();
;     QKT_PF(pA0, pA1, 0);
;     RS_BAR();
.LBB0_506:
	s_add_i32 s1, s0, s8
	s_add_i32 s4, s1, 32
	s_ashr_i32 s5, s4, 31
	s_lshl_b32 s48, s2, 5
	s_lshl_b64 s[4:5], s[4:5], 21
	s_add_u32 s46, s33, s4
	s_addc_u32 s47, s54, s5
	s_or_b32 s0, s0, s8
	s_ashr_i32 s1, s0, 31
	s_lshl_b64 s[0:1], s[0:1], 21
	s_add_u32 s0, s33, s0
	s_addc_u32 s1, s54, s1
	s_lshl_b32 s3, s3, 15
	s_add_u32 s0, s0, s3
	v_or_b32_e32 v0, s48, v178
	s_addc_u32 s1, s1, 0
	v_lshlrev_b32_e32 v0, 8, v0
	v_lshl_add_u64 v[2:3], s[0:1], 0, v[0:1]
	v_mov_b32_e32 v165, v1
	v_lshl_add_u64 v[2:3], v[2:3], 0, v[164:165]
	global_load_dwordx4 v[66:69], v[2:3], off
	global_load_dwordx4 v[70:73], v[2:3], off offset:32
	global_load_dwordx4 v[74:77], v[2:3], off offset:64
	global_load_dwordx4 v[78:81], v[2:3], off offset:96
	global_load_dwordx4 v[82:85], v[2:3], off offset:128
	global_load_dwordx4 v[86:89], v[2:3], off offset:160
	global_load_dwordx4 v[90:93], v[2:3], off offset:192
	global_load_dwordx4 v[94:97], v[2:3], off offset:224
	v_lshrrev_b32_e32 v0, 4, v180
	v_and_b32_e32 v2, 15, v181
	v_lshlrev_b32_e32 v4, 7, v0
	v_bitop3_b32 v3, v0, v181, 15 bitop3:0x78
	v_lshl_or_b32 v4, s2, 11, v4
	v_bitop3_b32 v0, v0, v2, 4 bitop3:0x36
	v_lshl_or_b32 v98, v3, 3, v4
	v_lshl_or_b32 v118, v0, 3, v4
	v_lshlrev_b32_e32 v2, 1, v118
	v_lshlrev_b32_e32 v0, 1, v98
	v_mov_b32_e32 v3, v1
	s_add_i32 s2, s64, 0x400
	s_add_i32 s3, s64, 0x800
	s_add_i32 s66, s64, 0xc00
	s_cmp_lg_u32 0, -1
	s_cselect_b32 s4, 0, 0
	s_add_u32 s0, s46, 0x4000
	s_addc_u32 s1, s47, 0
	s_add_i32 s67, s64, 0x4000
	s_add_i32 s68, s64, 0x4400
	s_add_i32 s69, s64, 0x4800
	s_add_i32 s70, s64, 0x4c00
	v_add_u32_e32 v4, 0x400, v2
	v_xor_b32_e32 v5, 0x80, v0
	v_add_u32_e32 v5, 0x800, v5
	v_xor_b32_e32 v6, 0x80, v2
	v_add_u32_e32 v6, 0xc00, v6
	s_mov_b32 m0, s64
	s_nop 0
	global_load_lds_dwordx4 v0, s[46:47]
	s_mov_b32 m0, s2
	s_nop 0
	global_load_lds_dwordx4 v4, s[46:47]
	s_mov_b32 m0, s3
	s_nop 0
	global_load_lds_dwordx4 v5, s[46:47]
	s_mov_b32 m0, s66
	s_nop 0
	global_load_lds_dwordx4 v6, s[46:47]
	s_mov_b32 m0, s67
	s_nop 0
	global_load_lds_dwordx4 v0, s[0:1]
	s_mov_b32 m0, s68
	s_nop 0
	global_load_lds_dwordx4 v4, s[0:1]
	s_mov_b32 m0, s69
	s_nop 0
	global_load_lds_dwordx4 v5, s[0:1]
	s_mov_b32 m0, s70
	s_nop 0
	global_load_lds_dwordx4 v6, s[0:1]
	v_lshlrev_b32_e32 v99, 8, v178
	v_lshlrev_b32_e32 v10, 4, v181
	v_and_b32_e32 v107, 0xf0, v10
	v_add_u32_e32 v108, s4, v99
	s_waitcnt vmcnt(0)
	v_bitop3_b32 v0, v164, v10, s57 bitop3:0x78
	s_waitcnt lgkmcnt(0)
	s_barrier
	v_add_u32_e32 v100, v0, v108
	ds_read_b128 v[2:5], v100
	ds_read_b128 v[6:9], v100 offset:8192
	v_bitop3_b32 v109, v164, v107, 32 bitop3:0x36
	v_bitop3_b32 v110, v164, v107, 64 bitop3:0x36
	v_bitop3_b32 v111, v164, v107, s58 bitop3:0x36
	v_add_u32_e32 v101, v109, v108
	ds_read_b128 v[34:37], v101
	ds_read_b128 v[38:41], v101 offset:8192
	v_add_u32_e32 v102, v110, v108
	ds_read_b128 v[42:45], v102
	ds_read_b128 v[46:49], v102 offset:8192
	v_add_u32_e32 v103, v111, v108
	ds_read_b128 v[50:53], v103
	ds_read_b128 v[54:57], v103 offset:8192
	s_waitcnt lgkmcnt(6)
	s_movk_i32 s0, 0x80
	s_waitcnt vmcnt(0)
	v_mfma_f32_32x32x16_bf16 v[18:33], v[2:5], v[66:69], 0
	v_bitop3_b32 v112, v164, v107, s0 bitop3:0x36
	v_add_u32_e32 v104, v112, v108
	ds_read_b128 v[58:61], v104
	ds_read_b128 v[62:65], v104 offset:8192
	s_waitcnt lgkmcnt(6)
	v_bitop3_b32 v114, v164, v107, s59 bitop3:0x36
	v_add_u32_e32 v105, v114, v108
	v_mfma_f32_32x32x16_bf16 v[2:17], v[6:9], v[66:69], 0
	s_movk_i32 s0, 0xc0
	v_bitop3_b32 v115, v164, v107, s0 bitop3:0x36
	v_add_u32_e32 v106, v115, v108
	v_bitop3_b32 v116, v164, v107, s60 bitop3:0x36
	v_add_u32_e32 v107, v116, v108
	s_addk_i32 s4, 0x4000
	s_mov_b32 s71, 0
	v_mfma_f32_32x32x16_bf16 v[18:33], v[34:37], v[70:73], v[18:33]
	ds_read_b128 v[34:37], v105
	v_cmp_gt_u32_e64 s[0:1], 32, v180
	v_lshl_add_u32 v117, v178, 2, s65
	v_mov_b32_e32 v121, 0xf149f2ca
	s_movk_i32 s72, 0x6000
	v_mfma_f32_32x32x16_bf16 v[2:17], v[38:41], v[70:73], v[2:17]
	ds_read_b128 v[38:41], v105 offset:8192
	s_waitcnt lgkmcnt(6)
	s_nop 0
	v_mfma_f32_32x32x16_bf16 v[18:33], v[42:45], v[74:77], v[18:33]
	ds_read_b128 v[42:45], v106
	v_mfma_f32_32x32x16_bf16 v[2:17], v[46:49], v[74:77], v[2:17]
	ds_read_b128 v[46:49], v106 offset:8192
	s_waitcnt lgkmcnt(6)
	s_nop 0
	v_mfma_f32_32x32x16_bf16 v[18:33], v[50:53], v[78:81], v[18:33]
	ds_read_b128 v[50:53], v107
	v_mfma_f32_32x32x16_bf16 v[2:17], v[54:57], v[78:81], v[2:17]
	ds_read_b128 v[54:57], v107 offset:8192
	s_waitcnt lgkmcnt(6)
	s_waitcnt lgkmcnt(4)
	s_waitcnt lgkmcnt(2)
	s_nop 0
	s_waitcnt lgkmcnt(0)
	s_waitcnt lgkmcnt(0)
	v_mfma_f32_32x32x16_bf16 v[18:33], v[58:61], v[82:85], v[18:33]
	s_barrier
	v_mfma_f32_32x32x16_bf16 v[2:17], v[62:65], v[82:85], v[2:17]
	v_mfma_f32_32x32x16_bf16 v[18:33], v[34:37], v[86:89], v[18:33]
	v_add_u32_e32 v34, s4, v99
	v_add_u32_e32 v108, v0, v34
	v_add_u32_e32 v109, v109, v34
	v_add_u32_e32 v110, v110, v34
	v_add_u32_e32 v111, v111, v34
	v_add_u32_e32 v113, v112, v34
	v_add_u32_e32 v114, v114, v34
	v_mfma_f32_32x32x16_bf16 v[2:17], v[38:41], v[86:89], v[2:17]
	v_add_u32_e32 v115, v115, v34
	v_add_u32_e32 v116, v116, v34
	v_cmp_eq_u32_e64 s[4:5], 0, v180
	v_mov_b32_e32 v112, 0
	v_lshlrev_b32_e32 v0, 1, v98
	v_lshlrev_b32_e32 v98, 1, v118
	v_mfma_f32_32x32x16_bf16 v[18:33], v[42:45], v[90:93], v[18:33]
	v_mfma_f32_32x32x16_bf16 v[2:17], v[46:49], v[90:93], v[2:17]
	v_mfma_f32_32x32x16_bf16 v[18:33], v[50:53], v[94:97], v[18:33]
	v_mfma_f32_32x32x16_bf16 v[2:17], v[54:57], v[94:97], v[2:17]
	v_add_u32_e32 v236, 0x400, v98
	v_xor_b32_e32 v237, 0x80, v0
	v_add_u32_e32 v237, 0x800, v237
	v_xor_b32_e32 v238, 0x80, v98
	v_add_u32_e32 v238, 0xc00, v238
	s_nop 7
	s_nop 7
	s_branch .LBB0_508
